# 256 s_nop executed by every wave right before each in-loop grid sync (on top of v16)
# baseline (speedup 1.0000x reference)
.LBB0_194:
	s_nop 0
	s_nop 0
	s_nop 0
	s_nop 0
	s_nop 0
	s_nop 0
	s_nop 0
	s_nop 0
	s_nop 0
	s_nop 0
	s_nop 0
	s_nop 0
	s_nop 0
	s_nop 0
	s_nop 0
	s_nop 0
	s_nop 0
	s_nop 0
	s_nop 0
	s_nop 0
	s_nop 0
	s_nop 0
	s_nop 0
	s_nop 0
	s_nop 0
	s_nop 0
	s_nop 0
	s_nop 0
	s_nop 0
	s_nop 0
	s_nop 0
	s_nop 0
	s_nop 0
	s_nop 0
	s_nop 0
	s_nop 0
	s_nop 0
	s_nop 0
	s_nop 0
	s_nop 0
	s_nop 0
	s_nop 0
	s_nop 0
	s_nop 0
	s_nop 0
	s_nop 0
	s_nop 0
	s_nop 0
	s_nop 0
	s_nop 0
	s_nop 0
	s_nop 0
	s_nop 0
	s_nop 0
	s_nop 0
	s_nop 0
	s_nop 0
	s_nop 0
	s_nop 0
	s_nop 0
	s_nop 0
	s_nop 0
	s_nop 0
	s_nop 0
	s_nop 0
	s_nop 0
	s_nop 0
	s_nop 0
	s_nop 0
	s_nop 0
	s_nop 0
	s_nop 0
	s_nop 0
	s_nop 0
	s_nop 0
	s_nop 0
	s_nop 0
	s_nop 0
	s_nop 0
	s_nop 0
	s_nop 0
	s_nop 0
	s_nop 0
	s_nop 0
	s_nop 0
	s_nop 0
	s_nop 0
	s_nop 0
	s_nop 0
	s_nop 0
	s_nop 0
	s_nop 0
	s_nop 0
	s_nop 0
	s_nop 0
	s_nop 0
	s_nop 0
	s_nop 0
	s_nop 0
	s_nop 0
	s_nop 0
	s_nop 0
	s_nop 0
	s_nop 0
	s_nop 0
	s_nop 0
	s_nop 0
	s_nop 0
	s_nop 0
	s_nop 0
	s_nop 0
	s_nop 0
	s_nop 0
	s_nop 0
	s_nop 0
	s_nop 0
	s_nop 0
	s_nop 0
	s_nop 0
	s_nop 0
	s_nop 0
	s_nop 0
	s_nop 0
	s_nop 0
	s_nop 0
	s_nop 0
	s_nop 0
	s_nop 0
	s_nop 0
	s_nop 0
	s_nop 0
	s_nop 0
	s_nop 0
	s_nop 0
	s_nop 0
	s_nop 0
	s_nop 0
	s_nop 0
	s_nop 0
	s_nop 0
	s_nop 0
	s_nop 0
	s_nop 0
	s_nop 0
	s_nop 0
	s_nop 0
	s_nop 0
	s_nop 0
	s_nop 0
	s_nop 0
	s_nop 0
	s_nop 0
	s_nop 0
	s_nop 0
	s_nop 0
	s_nop 0
	s_nop 0
	s_nop 0
	s_nop 0
	s_nop 0
	s_nop 0
	s_nop 0
	s_nop 0
	s_nop 0
	s_nop 0
	s_nop 0
	s_nop 0
	s_nop 0
	s_nop 0
	s_nop 0
	s_nop 0
	s_nop 0
	s_nop 0
	s_nop 0
	s_nop 0
	s_nop 0
	s_nop 0
	s_nop 0
	s_nop 0
	s_nop 0
	s_nop 0
	s_nop 0
	s_nop 0
	s_nop 0
	s_nop 0
	s_nop 0
	s_nop 0
	s_nop 0
	s_nop 0
	s_nop 0
	s_nop 0
	s_nop 0
	s_nop 0
	s_nop 0
	s_nop 0
	s_nop 0
	s_nop 0
	s_nop 0
	s_nop 0
	s_nop 0
	s_nop 0
	s_nop 0
	s_nop 0
	s_nop 0
	s_nop 0
	s_nop 0
	s_nop 0
	s_nop 0
	s_nop 0
	s_nop 0
	s_nop 0
	s_nop 0
	s_nop 0
	s_nop 0
	s_nop 0
	s_nop 0
	s_nop 0
	s_nop 0
	s_nop 0
	s_nop 0
	s_nop 0
	s_nop 0
	s_nop 0
	s_nop 0
	s_nop 0
	s_nop 0
	s_nop 0
	s_nop 0
	s_nop 0
	s_nop 0
	s_nop 0
	s_nop 0
	s_nop 0
	s_nop 0
	s_nop 0
	s_nop 0
	s_nop 0
	s_nop 0
	s_nop 0
	s_nop 0
	s_nop 0
	s_nop 0
	s_nop 0
	s_nop 0
	s_nop 0
	s_nop 0
	s_nop 0
	s_nop 0
	s_nop 0
	s_nop 0
	s_nop 0
	s_nop 0
	s_nop 0
	s_nop 0
	s_nop 0
	s_nop 0
	s_waitcnt vmcnt(0)
	s_barrier
	s_and_saveexec_b64 s[2:3], s[82:83]
	s_movk_i32 s56, 0x4000
	s_movk_i32 s57, 0x90
	s_movk_i32 s96, 0x1000
	s_movk_i32 s97, 0x408
	s_cbranch_execz .LBB0_246
	v_readlane_b32 s0, v253, 43
	s_waitcnt vmcnt(0) expcnt(0) lgkmcnt(0)
	s_nop 0
	v_mov_b32_e32 v0, s0
	ds_read_b32 v3, v0
	v_readlane_b32 s0, v253, 44
	s_waitcnt lgkmcnt(0)
	v_cmp_ne_u32_e32 vcc, 0, v3
	v_mov_b32_e32 v0, s0
	ds_read_b32 v2, v0
	s_cbranch_vccnz .LBB0_210
	s_mov_b32 s8, 1
	s_branch .LBB0_198

.LBB0_266:
	s_nop 0
	s_nop 0
	s_nop 0
	s_nop 0
	s_nop 0
	s_nop 0
	s_nop 0
	s_nop 0
	s_nop 0
	s_nop 0
	s_nop 0
	s_nop 0
	s_nop 0
	s_nop 0
	s_nop 0
	s_nop 0
	s_nop 0
	s_nop 0
	s_nop 0
	s_nop 0
	s_nop 0
	s_nop 0
	s_nop 0
	s_nop 0
	s_nop 0
	s_nop 0
	s_nop 0
	s_nop 0
	s_nop 0
	s_nop 0
	s_nop 0
	s_nop 0
	s_nop 0
	s_nop 0
	s_nop 0
	s_nop 0
	s_nop 0
	s_nop 0
	s_nop 0
	s_nop 0
	s_nop 0
	s_nop 0
	s_nop 0
	s_nop 0
	s_nop 0
	s_nop 0
	s_nop 0
	s_nop 0
	s_nop 0
	s_nop 0
	s_nop 0
	s_nop 0
	s_nop 0
	s_nop 0
	s_nop 0
	s_nop 0
	s_nop 0
	s_nop 0
	s_nop 0
	s_nop 0
	s_nop 0
	s_nop 0
	s_nop 0
	s_nop 0
	s_nop 0
	s_nop 0
	s_nop 0
	s_nop 0
	s_nop 0
	s_nop 0
	s_nop 0
	s_nop 0
	s_nop 0
	s_nop 0
	s_nop 0
	s_nop 0
	s_nop 0
	s_nop 0
	s_nop 0
	s_nop 0
	s_nop 0
	s_nop 0
	s_nop 0
	s_nop 0
	s_nop 0
	s_nop 0
	s_nop 0
	s_nop 0
	s_nop 0
	s_nop 0
	s_nop 0
	s_nop 0
	s_nop 0
	s_nop 0
	s_nop 0
	s_nop 0
	s_nop 0
	s_nop 0
	s_nop 0
	s_nop 0
	s_nop 0
	s_nop 0
	s_nop 0
	s_nop 0
	s_nop 0
	s_nop 0
	s_nop 0
	s_nop 0
	s_nop 0
	s_nop 0
	s_nop 0
	s_nop 0
	s_nop 0
	s_nop 0
	s_nop 0
	s_nop 0
	s_nop 0
	s_nop 0
	s_nop 0
	s_nop 0
	s_nop 0
	s_nop 0
	s_nop 0
	s_nop 0
	s_nop 0
	s_nop 0
	s_nop 0
	s_nop 0
	s_nop 0
	s_nop 0
	s_nop 0
	s_nop 0
	s_nop 0
	s_nop 0
	s_nop 0
	s_nop 0
	s_nop 0
	s_nop 0
	s_nop 0
	s_nop 0
	s_nop 0
	s_nop 0
	s_nop 0
	s_nop 0
	s_nop 0
	s_nop 0
	s_nop 0
	s_nop 0
	s_nop 0
	s_nop 0
	s_nop 0
	s_nop 0
	s_nop 0
	s_nop 0
	s_nop 0
	s_nop 0
	s_nop 0
	s_nop 0
	s_nop 0
	s_nop 0
	s_nop 0
	s_nop 0
	s_nop 0
	s_nop 0
	s_nop 0
	s_nop 0
	s_nop 0
	s_nop 0
	s_nop 0
	s_nop 0
	s_nop 0
	s_nop 0
	s_nop 0
	s_nop 0
	s_nop 0
	s_nop 0
	s_nop 0
	s_nop 0
	s_nop 0
	s_nop 0
	s_nop 0
	s_nop 0
	s_nop 0
	s_nop 0
	s_nop 0
	s_nop 0
	s_nop 0
	s_nop 0
	s_nop 0
	s_nop 0
	s_nop 0
	s_nop 0
	s_nop 0
	s_nop 0
	s_nop 0
	s_nop 0
	s_nop 0
	s_nop 0
	s_nop 0
	s_nop 0
	s_nop 0
	s_nop 0
	s_nop 0
	s_nop 0
	s_nop 0
	s_nop 0
	s_nop 0
	s_nop 0
	s_nop 0
	s_nop 0
	s_nop 0
	s_nop 0
	s_nop 0
	s_nop 0
	s_nop 0
	s_nop 0
	s_nop 0
	s_nop 0
	s_nop 0
	s_nop 0
	s_nop 0
	s_nop 0
	s_nop 0
	s_nop 0
	s_nop 0
	s_nop 0
	s_nop 0
	s_nop 0
	s_nop 0
	s_nop 0
	s_nop 0
	s_nop 0
	s_nop 0
	s_nop 0
	s_nop 0
	s_nop 0
	s_nop 0
	s_nop 0
	s_nop 0
	s_nop 0
	s_nop 0
	s_nop 0
	s_nop 0
	s_nop 0
	s_nop 0
	s_nop 0
	s_nop 0
	s_nop 0
	s_nop 0
	s_nop 0
	s_nop 0
	s_nop 0
	s_nop 0
	s_nop 0
	s_nop 0
	s_nop 0
	s_waitcnt vmcnt(0)
	s_waitcnt vmcnt(0)
	s_barrier
	s_and_saveexec_b64 s[2:3], s[82:83]
	s_cbranch_execz .LBB0_318
	v_readlane_b32 s0, v253, 43
	s_waitcnt vmcnt(0) expcnt(0) lgkmcnt(0)
	s_nop 0
	v_mov_b32_e32 v0, s0
	ds_read_b32 v3, v0
	v_readlane_b32 s0, v253, 44
	s_waitcnt lgkmcnt(0)
	v_cmp_ne_u32_e32 vcc, 0, v3
	v_mov_b32_e32 v0, s0
	ds_read_b32 v2, v0
	s_cbranch_vccnz .LBB0_282
	s_mov_b32 s8, 1
	s_branch .LBB0_270

.LBB0_360:
	s_nop 0
	s_nop 0
	s_nop 0
	s_nop 0
	s_nop 0
	s_nop 0
	s_nop 0
	s_nop 0
	s_nop 0
	s_nop 0
	s_nop 0
	s_nop 0
	s_nop 0
	s_nop 0
	s_nop 0
	s_nop 0
	s_nop 0
	s_nop 0
	s_nop 0
	s_nop 0
	s_nop 0
	s_nop 0
	s_nop 0
	s_nop 0
	s_nop 0
	s_nop 0
	s_nop 0
	s_nop 0
	s_nop 0
	s_nop 0
	s_nop 0
	s_nop 0
	s_nop 0
	s_nop 0
	s_nop 0
	s_nop 0
	s_nop 0
	s_nop 0
	s_nop 0
	s_nop 0
	s_nop 0
	s_nop 0
	s_nop 0
	s_nop 0
	s_nop 0
	s_nop 0
	s_nop 0
	s_nop 0
	s_nop 0
	s_nop 0
	s_nop 0
	s_nop 0
	s_nop 0
	s_nop 0
	s_nop 0
	s_nop 0
	s_nop 0
	s_nop 0
	s_nop 0
	s_nop 0
	s_nop 0
	s_nop 0
	s_nop 0
	s_nop 0
	s_nop 0
	s_nop 0
	s_nop 0
	s_nop 0
	s_nop 0
	s_nop 0
	s_nop 0
	s_nop 0
	s_nop 0
	s_nop 0
	s_nop 0
	s_nop 0
	s_nop 0
	s_nop 0
	s_nop 0
	s_nop 0
	s_nop 0
	s_nop 0
	s_nop 0
	s_nop 0
	s_nop 0
	s_nop 0
	s_nop 0
	s_nop 0
	s_nop 0
	s_nop 0
	s_nop 0
	s_nop 0
	s_nop 0
	s_nop 0
	s_nop 0
	s_nop 0
	s_nop 0
	s_nop 0
	s_nop 0
	s_nop 0
	s_nop 0
	s_nop 0
	s_nop 0
	s_nop 0
	s_nop 0
	s_nop 0
	s_nop 0
	s_nop 0
	s_nop 0
	s_nop 0
	s_nop 0
	s_nop 0
	s_nop 0
	s_nop 0
	s_nop 0
	s_nop 0
	s_nop 0
	s_nop 0
	s_nop 0
	s_nop 0
	s_nop 0
	s_nop 0
	s_nop 0
	s_nop 0
	s_nop 0
	s_nop 0
	s_nop 0
	s_nop 0
	s_nop 0
	s_nop 0
	s_nop 0
	s_nop 0
	s_nop 0
	s_nop 0
	s_nop 0
	s_nop 0
	s_nop 0
	s_nop 0
	s_nop 0
	s_nop 0
	s_nop 0
	s_nop 0
	s_nop 0
	s_nop 0
	s_nop 0
	s_nop 0
	s_nop 0
	s_nop 0
	s_nop 0
	s_nop 0
	s_nop 0
	s_nop 0
	s_nop 0
	s_nop 0
	s_nop 0
	s_nop 0
	s_nop 0
	s_nop 0
	s_nop 0
	s_nop 0
	s_nop 0
	s_nop 0
	s_nop 0
	s_nop 0
	s_nop 0
	s_nop 0
	s_nop 0
	s_nop 0
	s_nop 0
	s_nop 0
	s_nop 0
	s_nop 0
	s_nop 0
	s_nop 0
	s_nop 0
	s_nop 0
	s_nop 0
	s_nop 0
	s_nop 0
	s_nop 0
	s_nop 0
	s_nop 0
	s_nop 0
	s_nop 0
	s_nop 0
	s_nop 0
	s_nop 0
	s_nop 0
	s_nop 0
	s_nop 0
	s_nop 0
	s_nop 0
	s_nop 0
	s_nop 0
	s_nop 0
	s_nop 0
	s_nop 0
	s_nop 0
	s_nop 0
	s_nop 0
	s_nop 0
	s_nop 0
	s_nop 0
	s_nop 0
	s_nop 0
	s_nop 0
	s_nop 0
	s_nop 0
	s_nop 0
	s_nop 0
	s_nop 0
	s_nop 0
	s_nop 0
	s_nop 0
	s_nop 0
	s_nop 0
	s_nop 0
	s_nop 0
	s_nop 0
	s_nop 0
	s_nop 0
	s_nop 0
	s_nop 0
	s_nop 0
	s_nop 0
	s_nop 0
	s_nop 0
	s_nop 0
	s_nop 0
	s_nop 0
	s_nop 0
	s_nop 0
	s_nop 0
	s_nop 0
	s_nop 0
	s_nop 0
	s_nop 0
	s_nop 0
	s_nop 0
	s_nop 0
	s_nop 0
	s_nop 0
	s_nop 0
	s_nop 0
	s_nop 0
	s_nop 0
	s_nop 0
	s_nop 0
	s_nop 0
	s_nop 0
	s_nop 0
	s_nop 0
	s_nop 0
	s_nop 0
	s_nop 0
	s_nop 0
	s_waitcnt vmcnt(0)
	s_barrier
	s_and_saveexec_b64 s[2:3], s[82:83]
	s_cbranch_execz .LBB0_458
	v_readlane_b32 s0, v253, 43
	s_waitcnt vmcnt(0) expcnt(0) lgkmcnt(0)
	s_nop 0
	v_mov_b32_e32 v0, s0
	ds_read_b32 v3, v0
	v_readlane_b32 s0, v253, 44
	s_waitcnt lgkmcnt(0)
	v_cmp_ne_u32_e32 vcc, 0, v3
	v_mov_b32_e32 v0, s0
	ds_read_b32 v2, v0
	s_cbranch_vccnz .LBB0_422
	s_mov_b32 s8, 1
	s_branch .LBB0_410

.LBB0_1271:
	s_nop 0
	s_nop 0
	s_nop 0
	s_nop 0
	s_nop 0
	s_nop 0
	s_nop 0
	s_nop 0
	s_nop 0
	s_nop 0
	s_nop 0
	s_nop 0
	s_nop 0
	s_nop 0
	s_nop 0
	s_nop 0
	s_nop 0
	s_nop 0
	s_nop 0
	s_nop 0
	s_nop 0
	s_nop 0
	s_nop 0
	s_nop 0
	s_nop 0
	s_nop 0
	s_nop 0
	s_nop 0
	s_nop 0
	s_nop 0
	s_nop 0
	s_nop 0
	s_nop 0
	s_nop 0
	s_nop 0
	s_nop 0
	s_nop 0
	s_nop 0
	s_nop 0
	s_nop 0
	s_nop 0
	s_nop 0
	s_nop 0
	s_nop 0
	s_nop 0
	s_nop 0
	s_nop 0
	s_nop 0
	s_nop 0
	s_nop 0
	s_nop 0
	s_nop 0
	s_nop 0
	s_nop 0
	s_nop 0
	s_nop 0
	s_nop 0
	s_nop 0
	s_nop 0
	s_nop 0
	s_nop 0
	s_nop 0
	s_nop 0
	s_nop 0
	s_nop 0
	s_nop 0
	s_nop 0
	s_nop 0
	s_nop 0
	s_nop 0
	s_nop 0
	s_nop 0
	s_nop 0
	s_nop 0
	s_nop 0
	s_nop 0
	s_nop 0
	s_nop 0
	s_nop 0
	s_nop 0
	s_nop 0
	s_nop 0
	s_nop 0
	s_nop 0
	s_nop 0
	s_nop 0
	s_nop 0
	s_nop 0
	s_nop 0
	s_nop 0
	s_nop 0
	s_nop 0
	s_nop 0
	s_nop 0
	s_nop 0
	s_nop 0
	s_nop 0
	s_nop 0
	s_nop 0
	s_nop 0
	s_nop 0
	s_nop 0
	s_nop 0
	s_nop 0
	s_nop 0
	s_nop 0
	s_nop 0
	s_nop 0
	s_nop 0
	s_nop 0
	s_nop 0
	s_nop 0
	s_nop 0
	s_nop 0
	s_nop 0
	s_nop 0
	s_nop 0
	s_nop 0
	s_nop 0
	s_nop 0
	s_nop 0
	s_nop 0
	s_nop 0
	s_nop 0
	s_nop 0
	s_nop 0
	s_nop 0
	s_nop 0
	s_nop 0
	s_nop 0
	s_nop 0
	s_nop 0
	s_nop 0
	s_nop 0
	s_nop 0
	s_nop 0
	s_nop 0
	s_nop 0
	s_nop 0
	s_nop 0
	s_nop 0
	s_nop 0
	s_nop 0
	s_nop 0
	s_nop 0
	s_nop 0
	s_nop 0
	s_nop 0
	s_nop 0
	s_nop 0
	s_nop 0
	s_nop 0
	s_nop 0
	s_nop 0
	s_nop 0
	s_nop 0
	s_nop 0
	s_nop 0
	s_nop 0
	s_nop 0
	s_nop 0
	s_nop 0
	s_nop 0
	s_nop 0
	s_nop 0
	s_nop 0
	s_nop 0
	s_nop 0
	s_nop 0
	s_nop 0
	s_nop 0
	s_nop 0
	s_nop 0
	s_nop 0
	s_nop 0
	s_nop 0
	s_nop 0
	s_nop 0
	s_nop 0
	s_nop 0
	s_nop 0
	s_nop 0
	s_nop 0
	s_nop 0
	s_nop 0
	s_nop 0
	s_nop 0
	s_nop 0
	s_nop 0
	s_nop 0
	s_nop 0
	s_nop 0
	s_nop 0
	s_nop 0
	s_nop 0
	s_nop 0
	s_nop 0
	s_nop 0
	s_nop 0
	s_nop 0
	s_nop 0
	s_nop 0
	s_nop 0
	s_nop 0
	s_nop 0
	s_nop 0
	s_nop 0
	s_nop 0
	s_nop 0
	s_nop 0
	s_nop 0
	s_nop 0
	s_nop 0
	s_nop 0
	s_nop 0
	s_nop 0
	s_nop 0
	s_nop 0
	s_nop 0
	s_nop 0
	s_nop 0
	s_nop 0
	s_nop 0
	s_nop 0
	s_nop 0
	s_nop 0
	s_nop 0
	s_nop 0
	s_nop 0
	s_nop 0
	s_nop 0
	s_nop 0
	s_nop 0
	s_nop 0
	s_nop 0
	s_nop 0
	s_nop 0
	s_nop 0
	s_nop 0
	s_nop 0
	s_nop 0
	s_nop 0
	s_nop 0
	s_nop 0
	s_nop 0
	s_nop 0
	s_nop 0
	s_nop 0
	s_nop 0
	s_nop 0
	s_nop 0
	s_nop 0
	s_nop 0
	s_nop 0
	s_nop 0
	s_nop 0
	s_waitcnt vmcnt(0)
	s_barrier
	s_and_saveexec_b64 s[2:3], s[82:83]
	s_cbranch_execnz .LBB0_1272
	s_getpc_b64 s[98:99]
